# P3: cmp tickets ordered heaviest first (the tg quarter with the most compressed-key subtiles is drawn first)
# speedup vs baseline: 1.0068x; 1.0009x over previous
; #define MFMA32(a, b, c) __builtin_amdgcn_mfma_f32_32x32x16_bf16((a), (b), (c), 0, 0, 0)
; DI int crow(int r, int h) { return (r & 3) + 8 * (r >> 2) + 4 * h; }
; DI void cmp_task(const bf16_t* Z, const bf16_t* KCC, const bf16_t* VCT, bf16_t* OCMP, unsigned* selm, int b, int hk, int tg, int lane) {
;     const int r32 = lane & 31, h = lane >> 5;
;     const int tok = 8 * tg + (r32 >> 2), g = r32 & 3, head = hk * 4 + g;
;     const size_t grow = (size_t)b * SEQ + tok;
;     const bf16_t* zr = Z + grow * NZ;
;     bf16x8 qf[4];
; #pragma unroll
;     for (int s = 0; s < 4; ++s) qf[s] = *(const bf16x8*)(zr + ZC_QA + head * 64 + 16 * s + 8 * h);
;     const bf16_t* kc = KCC + (size_t)(b * 2 + hk) * 128 * 64; const bf16_t* vt = VCT + (size_t)(b * 2 + hk) * 64 * 128;
;     const int tmax = 8 * tg + 7;
;     const int nsub = tmax < 31 ? 0 : (((tmax - 31) >> 4) >> 5) + 1;
;     f32x16 p[4];
; #pragma unroll
;     for (int sub = 0; sub < 4; ++sub) {
;         if (sub < nsub) {
;             p[sub] = f16zero();
; #pragma unroll
;             for (int s = 0; s < 4; ++s) { const bf16x8 af = *(const bf16x8*)(kc + (size_t)(32 * sub + r32) * 64 + 16 * s + 8 * h); p[sub] = MFMA32(af, qf[s], p[sub]); }
; #pragma unroll
;             for (int r = 0; r < 16; ++r) { const int n = 32 * sub + crow(r, h); p[sub][r] = (16 * n + 31 <= tok) ? p[sub][r] * SM_C : NINF; }
; __global__ void __launch_bounds__(NTHR, 2) fwd_kernel(Args a) {
;     ...
;             if (ci < ncmp && (i >= nrow || (i % stride) == phase)) { const int task = gw + ci * NGW; ++ci;
;                 cmp_task(Z, KCC, VCT, OCMP, SELM, task >> 9, (task >> 8) & 1, (task + 64 * (task >> 11)) & 255, lane); }
.Lcmp_have:
	s_and_b32 s9, s8, 7
	s_lshr_b32 s8, s8, 3
	s_lshr_b32 s10, s92, 6
	s_add_i32 s8, s8, s10
	s_sub_i32 s8, 3, s8
	s_and_b32 s8, s8, 3
	s_lshl_b32 s8, s8, 11
	s_add_i32 s9, s9, s8
	s_and_b32 s8, s92, -8
	s_add_i32 s9, s9, s8
	s_lshr_b32 s10, s9, 5
	s_and_b32 s10, s10, 0xc0
	s_add_i32 s10, s10, s9
	s_ashr_i32 s8, s9, 9
	s_and_b32 s54, s10, 0xff
	s_bfe_u32 s14, s9, 0x10008
	s_lshl_b32 s50, s54, 3
	s_ashr_i32 s9, s8, 31
	v_or_b32_e32 v131, s50, v113
	s_lshl_b64 s[10:11], s[8:9], 11
	v_or_b32_e32 v122, s10, v131
	v_mov_b64_e32 v[2:3], s[22:23]
	s_movk_i32 s9, 0x2200
	v_mad_u64_u32 v[2:3], s[48:49], v122, s9, v[2:3]
	v_lshl_or_b32 v1, s14, 8, v115
	v_mad_i32_i24 v3, s11, v244, v3
	v_lshlrev_b32_e32 v42, 1, v1
	v_lshl_add_u64 v[2:3], v[2:3], 0, v[42:43]
	v_mov_b32_e32 v41, v43
	v_lshl_add_u64 v[2:3], v[2:3], 0, v[40:41]
	global_load_dwordx4 v[30:33], v[2:3], off
	global_load_dwordx4 v[26:29], v[2:3], off offset:32
	global_load_dwordx4 v[22:25], v[2:3], off offset:64
	global_load_dwordx4 v[18:21], v[2:3], off offset:96
	s_lshl_b32 s8, s8, 1
	s_or_b32 s8, s8, s14
	s_ashr_i32 s9, s8, 31
	s_lshl_b64 s[8:9], s[8:9], 14
	s_or_b32 s10, s50, 7
	s_cmp_lt_u32 s10, 31
	s_cselect_b64 s[48:49], -1, 0
	s_cmp_gt_u32 s10, 30
	v_mov_b32_e32 v123, s11
	s_cselect_b64 s[10:11], -1, 0
	v_lshl_add_u64 v[124:125], v[44:45], 0, s[8:9]
	v_mov_b32_e32 v121, 0xff800000
	s_and_b64 vcc, exec, s[48:49]
	v_lshlrev_b32_e32 v126, 1, v38
	v_mov_b32_e32 v128, 0xff800000
	v_mov_b32_e32 v129, 0xff800000
	v_mov_b32_e32 v130, 0xff800000
	v_mov_b32_e32 v134, 0xff800000
	v_mov_b32_e32 v135, 0xff800000
	v_mov_b32_e32 v139, 0xff800000
	v_mov_b32_e32 v140, 0xff800000
	v_mov_b32_e32 v141, 0xff800000
	v_mov_b32_e32 v142, 0xff800000
	v_mov_b32_e32 v143, 0xff800000
	v_mov_b32_e32 v144, 0xff800000
	v_mov_b32_e32 v145, 0xff800000
	v_mov_b32_e32 v146, 0xff800000
	v_mov_b32_e32 v147, 0xff800000
	v_mov_b32_e32 v148, 0xff800000
	v_mov_b32_e32 v149, 0xff800000
	s_cbranch_vccnz .LBB0_483
	v_mov_b32_e32 v127, v43
	v_lshl_add_u64 v[94:95], v[124:125], 0, v[126:127]
	global_load_dwordx4 v[2:5], v[94:95], off
	global_load_dwordx4 v[140:143], v[94:95], off offset:32
	global_load_dwordx4 v[150:153], v[94:95], off offset:64
	global_load_dwordx4 v[154:157], v[94:95], off offset:96
	v_cmp_le_u32_e32 vcc, v46, v131
	s_waitcnt vmcnt(3)
	v_mfma_f32_32x32x16_bf16 v[2:17], v[2:5], v[30:33], 0
	s_waitcnt vmcnt(2)
	v_mfma_f32_32x32x16_bf16 v[2:17], v[140:143], v[26:29], v[2:17]
	s_waitcnt vmcnt(1)
	v_mfma_f32_32x32x16_bf16 v[2:17], v[150:153], v[22:25], v[2:17]
	s_waitcnt vmcnt(0)
	v_mfma_f32_32x32x16_bf16 v[2:17], v[154:157], v[18:21], v[2:17]
	s_nop 11
	v_pk_mul_f32 v[2:3], v[2:3], s[46:47] op_sel_hi:[1,0]
	s_nop 0
	v_cndmask_b32_e32 v128, v245, v2, vcc
	v_cmp_le_u32_e32 vcc, v37, v131
	v_mul_f32_e32 v1, 0x3e38aa3b, v4
	s_nop 0
	v_cndmask_b32_e32 v129, v245, v3, vcc
	v_cmp_le_u32_e32 vcc, v117, v131
	v_pk_mul_f32 v[2:3], v[6:7], s[46:47] op_sel_hi:[1,0]
	s_nop 0
	v_cndmask_b32_e32 v130, v245, v1, vcc
	v_mul_f32_e32 v1, 0x3e38aa3b, v5
	v_cmp_le_u32_e32 vcc, v119, v131
	s_nop 1
	v_cndmask_b32_e32 v134, v245, v1, vcc
	v_cmp_le_u32_e32 vcc, v48, v131
	v_mul_f32_e32 v1, 0x3e38aa3b, v8
	s_nop 0
	v_cndmask_b32_e32 v135, v245, v2, vcc
	v_cmp_le_u32_e32 vcc, v39, v131
	s_nop 1
	v_cndmask_b32_e32 v139, v245, v3, vcc
	v_cmp_le_u32_e32 vcc, v202, v131
	v_pk_mul_f32 v[2:3], v[10:11], s[46:47] op_sel_hi:[1,0]
	s_nop 0
	v_cndmask_b32_e32 v140, v245, v1, vcc
	v_mul_f32_e32 v1, 0x3e38aa3b, v9
	v_cmp_le_u32_e32 vcc, v203, v131
	s_nop 1
	v_cndmask_b32_e32 v141, v245, v1, vcc
	v_cmp_le_u32_e32 vcc, v50, v131
	v_mul_f32_e32 v1, 0x3e38aa3b, v12
	s_nop 0
	v_cndmask_b32_e32 v142, v245, v2, vcc
	v_cmp_le_u32_e32 vcc, v47, v131
	s_nop 1
	v_cndmask_b32_e32 v143, v245, v3, vcc
	v_cmp_le_u32_e32 vcc, v204, v131
	v_pk_mul_f32 v[2:3], v[14:15], s[46:47] op_sel_hi:[1,0]
	s_nop 0
	v_cndmask_b32_e32 v144, v245, v1, vcc
	v_mul_f32_e32 v1, 0x3e38aa3b, v13
	v_cmp_le_u32_e32 vcc, v205, v131
	s_nop 1
	v_cndmask_b32_e32 v145, v245, v1, vcc
	v_cmp_le_u32_e32 vcc, v52, v131
	v_mul_f32_e32 v1, 0x3e38aa3b, v16
	s_nop 0
	v_cndmask_b32_e32 v146, v245, v2, vcc
	v_cmp_le_u32_e32 vcc, v49, v131
	s_nop 1
	v_cndmask_b32_e32 v147, v245, v3, vcc
	v_cmp_le_u32_e32 vcc, v206, v131
	s_nop 1
	v_cndmask_b32_e32 v148, v245, v1, vcc
	v_mul_f32_e32 v1, 0x3e38aa3b, v17
	v_cmp_le_u32_e32 vcc, v207, v131
	s_nop 1
	v_cndmask_b32_e32 v149, v245, v1, vcc
